# panel exchanges without the L2 write-back: partial records (FF2) and X tiles (out_proj, pool) are stored write-through (sc1), every wave drains, then the arrival count
# speedup vs baseline: 1.0489x; 1.0152x over previous
.LBB0_1246:
	s_cmpk_lt_u32 s42, 0xc0
	s_cselect_b64 s[16:17], -1, 0
	s_cmpk_gt_u32 s42, 0xbf
	s_cselect_b64 s[4:5], -1, 0
	s_and_b64 s[4:5], s[14:15], s[4:5]
	v_cndmask_b32_e64 v0, 0, 1, s[4:5]
	v_cmp_ne_u32_e64 s[6:7], 1, v0
	s_andn2_b64 vcc, exec, s[4:5]
	s_cbranch_vccnz .LBB0_1270
	s_lshr_b32 s4, s3, 29
	s_add_i32 s4, s2, s4
	s_ashr_i32 s5, s4, 3
	s_and_b32 s4, s4, -8
	s_sub_i32 s4, s2, s4
	s_lshr_b32 s10, s4, 31
	s_or_b32 s10, s10, 24
	s_mul_i32 s4, s10, s4
	s_add_i32 s4, s4, s5
	s_ashr_i32 s5, s4, 31
	s_lshr_b32 s5, s5, 27
	s_add_i32 s5, s4, s5
	s_ashr_i32 s24, s5, 5
	s_lshl_b32 s10, s24, 3
	s_sub_i32 s5, 48, s10
	s_min_u32 s11, s5, 8
	s_lshl_b32 s5, s24, 5
	s_sub_i32 s18, s4, s5
	s_sext_i32_i8 s4, s18
	v_cvt_f32_ubyte0_e32 v1, s11
	v_cvt_f32_i32_e32 v0, s4
	v_rcp_iflag_f32_e32 v2, v1
	s_ashr_i32 s4, s4, 30
	s_or_b32 s19, s4, 1
	v_mul_f32_e32 v2, v0, v2
	v_trunc_f32_e32 v2, v2
	v_fma_f32 v0, -v2, v1, v0
	v_cvt_i32_f32_e32 v2, v2
	v_cmp_ge_f32_e64 s[4:5], |v0|, v1
	s_and_b64 s[4:5], s[4:5], exec
	s_cselect_b32 s4, s19, 0
	v_readfirstlane_b32 s26, v2
	s_add_i32 s26, s26, s4
	s_mul_i32 s4, s26, s11
	s_sub_i32 s4, s18, s4
	s_sext_i32_i8 s25, s4
	s_add_i32 s4, s10, s25
	s_and_saveexec_b64 s[10:11], s[38:39]
	s_cbranch_execz .LBB0_1259
	s_ashr_i32 s5, s4, 31
	s_lshl_b64 s[18:19], s[4:5], 2
	s_mov_b64 s[20:21], exec
	s_add_u32 s5, s8, s18
	s_addc_u32 s19, s9, s19
	s_waitcnt vmcnt(0) lgkmcnt(0)
	s_waitcnt vmcnt(0)
	v_mbcnt_lo_u32_b32 v0, s20, 0
	s_add_u32 s18, s5, 0x779b800
	v_mbcnt_hi_u32_b32 v0, s21, v0
	s_addc_u32 s19, s19, 0
	v_cmp_eq_u32_e32 vcc, 0, v0
	s_and_saveexec_b64 s[22:23], vcc
	s_cbranch_execz .LBB0_1250
	s_bcnt1_i32_b64 s5, s[20:21]
	v_mov_b32_e32 v0, 0
	v_mov_b32_e32 v1, s5
	global_atomic_add v0, v1, s[18:19]

.Lf2p10_nop:
	s_waitcnt vmcnt(0)
	s_barrier
	s_and_saveexec_b64 s[14:15], s[38:39]
	s_cbranch_execz .LBB0_1479
	s_ashr_i32 s13, s12, 31
	s_lshl_b64 s[16:17], s[12:13], 2
	s_mov_b64 s[18:19], exec
	s_add_u32 s13, s22, s16
	s_addc_u32 s17, s23, s17
	s_waitcnt vmcnt(0) lgkmcnt(0)
	s_waitcnt vmcnt(0)
	v_mbcnt_lo_u32_b32 v0, s18, 0
	s_add_u32 s16, s13, 0x779b900
	v_mbcnt_hi_u32_b32 v0, s19, v0
	s_addc_u32 s17, s17, 0
	v_cmp_eq_u32_e32 vcc, 0, v0
	s_and_saveexec_b64 s[26:27], vcc
	s_cbranch_execz .LBB0_1470
	s_bcnt1_i32_b64 s13, s[18:19]
	v_mov_b32_e32 v0, 0
	v_mov_b32_e32 v1, s13
	global_atomic_add v0, v1, s[16:17]

.LBB0_1835:
	s_and_b64 vcc, exec, s[6:7]
	s_cbranch_vccnz .LBB0_1859
	s_lshr_b32 s12, s3, 29
	s_add_i32 s12, s2, s12
	s_ashr_i32 s13, s12, 3
	s_and_b32 s12, s12, -8
	s_sub_i32 s12, s2, s12
	s_lshr_b32 s20, s12, 31
	s_or_b32 s20, s20, 24
	s_mul_i32 s12, s20, s12
	s_add_i32 s12, s12, s13
	s_ashr_i32 s13, s12, 31
	s_lshr_b32 s13, s13, 27
	s_add_i32 s13, s12, s13
	s_ashr_i32 s28, s13, 5
	s_lshl_b32 s20, s28, 3
	s_sub_i32 s13, 48, s20
	s_min_u32 s21, s13, 8
	s_lshl_b32 s13, s28, 5
	s_sub_i32 s22, s12, s13
	s_sext_i32_i8 s12, s22
	v_cvt_f32_ubyte0_e32 v1, s21
	v_cvt_f32_i32_e32 v0, s12
	v_rcp_iflag_f32_e32 v2, v1
	s_ashr_i32 s12, s12, 30
	s_or_b32 s23, s12, 1
	v_mul_f32_e32 v2, v0, v2
	v_trunc_f32_e32 v2, v2
	v_fma_f32 v0, -v2, v1, v0
	v_cvt_i32_f32_e32 v2, v2
	v_cmp_ge_f32_e64 s[12:13], |v0|, v1
	s_and_b64 s[12:13], s[12:13], exec
	s_cselect_b32 s12, s23, 0
	v_readfirstlane_b32 s30, v2
	s_add_i32 s30, s30, s12
	s_mul_i32 s12, s30, s21
	s_sub_i32 s12, s22, s12
	s_sext_i32_i8 s29, s12
	s_add_i32 s12, s20, s29
	s_and_saveexec_b64 s[20:21], s[38:39]
	s_cbranch_execz .LBB0_1848
	s_ashr_i32 s13, s12, 31
	s_lshl_b64 s[22:23], s[12:13], 2
	s_mov_b64 s[24:25], exec
	s_add_u32 s13, s14, s22
	s_addc_u32 s23, s15, s23
	s_waitcnt vmcnt(0)
	s_waitcnt vmcnt(0)
	v_mbcnt_lo_u32_b32 v0, s24, 0
	s_add_u32 s22, s13, 0x779ba00
	v_mbcnt_hi_u32_b32 v0, s25, v0
	s_addc_u32 s23, s23, 0
	v_cmp_eq_u32_e32 vcc, 0, v0
	s_and_saveexec_b64 s[26:27], vcc
	s_cbranch_execz .LBB0_1839
	s_bcnt1_i32_b64 s13, s[24:25]
	v_mov_b32_e32 v0, 0
	v_mov_b32_e32 v1, s13
	global_atomic_add v0, v1, s[22:23]

.Lf2p16_nop:
	s_waitcnt vmcnt(0)
	s_barrier
	s_and_saveexec_b64 s[6:7], s[38:39]
	s_cbranch_execz .LBB0_2067
	s_ashr_i32 s3, s2, 31
	s_lshl_b64 s[8:9], s[2:3], 2
	s_mov_b64 s[10:11], exec
	s_add_u32 s3, s16, s8
	s_addc_u32 s9, s17, s9
	s_waitcnt vmcnt(0) lgkmcnt(0)
	s_waitcnt vmcnt(0)
	v_mbcnt_lo_u32_b32 v0, s10, 0
	s_add_u32 s8, s3, 0x779bb00
	v_mbcnt_hi_u32_b32 v0, s11, v0
	s_addc_u32 s9, s9, 0
	v_cmp_eq_u32_e32 vcc, 0, v0
	s_and_saveexec_b64 s[18:19], vcc
	s_cbranch_execz .LBB0_2058
	s_bcnt1_i32_b64 s3, s[10:11]
	v_mov_b32_e32 v0, 0
	v_mov_b32_e32 v1, s3
	global_atomic_add v0, v1, s[8:9]
